# stack: attention-A reschedule + GEMM LDS-DMA loads via SGPR base (no per-load 64-bit VALU add) + window-attn bias reads batched + L1 invalidate issued before barrier spin + rope/transposes XCD-local w
# speedup vs baseline: 1.0104x; 1.0104x over previous
; #define LAS __attribute__((address_space(3)))
; template <int HD, int MODE> ...
;     ...
;             if constexpr (HD == 64) {
;                 bf16x8 kf0[HD / 16], kf1[HD / 16];
; #pragma unroll
;                 for (int d0 = 0; d0 < HD / 16; ++d0) { kf0[d0] = *(const LAS bf16x8*)(kb + d0 * 32); kf1[d0] = *(const LAS bf16x8*)(kb + 32 * KROW + d0 * 32); }
;                 __builtin_amdgcn_sched_barrier(0);
;                 __builtin_amdgcn_s_setprio(1);
; #pragma unroll
;                 for (int d0 = 0; d0 < HD / 16; ++d0) { s0 = __builtin_amdgcn_mfma_f32_32x32x16_bf16(kf0[d0], qf[d0], s0, 0, 0, 0); s1 = __builtin_amdgcn_mfma_f32_32x32x16_bf16(kf1[d0], qf[d0], s1, 0, 0, 0); }
;                 __builtin_amdgcn_s_setprio(0);
;             } else {
;             __builtin_amdgcn_s_setprio(1);
; #pragma unroll
;             for (int d0 = 0; d0 < HD / 16; ++d0) {
;                 const bf16x8 k0 = *(const LAS bf16x8*)(kb + d0 * 32);
;                 const bf16x8 k1 = *(const LAS bf16x8*)(kb + 32 * KROW + d0 * 32);
;                 s0 = __builtin_amdgcn_mfma_f32_32x32x16_bf16(k0, qf[d0], s0, 0, 0, 0);
;                 s1 = __builtin_amdgcn_mfma_f32_32x32x16_bf16(k1, qf[d0], s1, 0, 0, 0);
;             }
;             __builtin_amdgcn_s_setprio(0); }
;             if (MODE == 1) {
;                 const LAS float* bl = biasl + (64 * t + 8 * hi - (qlo + r32) + 384);
; #pragma unroll
;                 for (int r = 0; r < 16; ++r) { s0[r] += bl[16 * (r >> 3) + (r & 7)]; s1[r] += bl[32 + 16 * (r >> 3) + (r & 7)]; }
;             }
;             float mx = fmaxf(s0[0], s1[0]);
; #pragma unroll
;             for (int r = 1; r < 16; ++r) mx = fmaxf(mx, fmaxf(s0[r], s1[r]));
;             { auto rr = __builtin_amdgcn_permlane32_swap(__float_as_uint(mx), __float_as_uint(mx), false, false); mx = fmaxf(__uint_as_float(rr[0]), __uint_as_float(rr[1])); }
.LBB0_520:
	s_add_i32 s29, s6, 63
	s_cmp_ge_i32 s29, s10
	s_cselect_b64 s[46:47], -1, 0
	s_cmp_le_i32 s6, s11
	s_cselect_b64 s[48:49], -1, 0
	s_and_b64 s[46:47], s[46:47], s[48:49]
	s_andn2_b64 vcc, exec, s[46:47]
	s_cbranch_vccnz .LBB0_524
	s_mul_i32 s29, s17, 0x4800
	s_add_i32 s29, s29, 0
	v_add3_u32 v38, s29, v95, v0
	ds_read_b128 v[34:37], v38
	ds_read_b128 v[104:107], v38 offset:32
	ds_read_b128 v[50:53], v38 offset:4608
	ds_read_b128 v[108:111], v38 offset:4640
	ds_read_b128 v[112:115], v38 offset:64
	ds_read_b128 v[116:119], v38 offset:96
	ds_read_b128 v[120:123], v38 offset:4672
	ds_read_b128 v[124:127], v38 offset:4704
	s_setprio 1
	s_waitcnt lgkmcnt(7)
	v_mfma_f32_32x32x16_bf16 v[34:49], v[34:37], v[66:69], 0
	s_waitcnt lgkmcnt(5)
	v_mfma_f32_32x32x16_bf16 v[50:65], v[50:53], v[66:69], 0
	v_mfma_f32_32x32x16_bf16 v[34:49], v[104:107], v[70:73], v[34:49]
	s_waitcnt lgkmcnt(4)
	v_mfma_f32_32x32x16_bf16 v[50:65], v[108:111], v[70:73], v[50:65]
	s_waitcnt lgkmcnt(3)
	v_mfma_f32_32x32x16_bf16 v[34:49], v[112:115], v[74:77], v[34:49]
	s_waitcnt lgkmcnt(1)
	v_mfma_f32_32x32x16_bf16 v[50:65], v[120:123], v[74:77], v[50:65]
	ds_read2_b32 v[130:131], v100 offset1:1
	ds_read2_b32 v[132:133], v100 offset0:32 offset1:33
	ds_read2_b32 v[134:135], v100 offset0:2 offset1:3
	ds_read2_b32 v[136:137], v100 offset0:34 offset1:35
	ds_read2_b32 v[138:139], v100 offset0:4 offset1:5
	ds_read2_b32 v[140:141], v100 offset0:36 offset1:37
	ds_read2_b32 v[142:143], v100 offset0:6 offset1:7
	ds_read2_b32 v[144:145], v100 offset0:38 offset1:39
	ds_read2_b32 v[146:147], v100 offset0:16 offset1:17
	ds_read2_b32 v[148:149], v100 offset0:48 offset1:49
	ds_read2_b32 v[150:151], v100 offset0:18 offset1:19
	ds_read2_b32 v[152:153], v100 offset0:50 offset1:51
	ds_read2_b32 v[154:155], v100 offset0:20 offset1:21
	ds_read2_b32 v[156:157], v100 offset0:52 offset1:53
	v_mfma_f32_32x32x16_bf16 v[34:49], v[116:119], v[78:81], v[34:49]
	s_waitcnt lgkmcnt(14)
	v_mfma_f32_32x32x16_bf16 v[50:65], v[124:127], v[78:81], v[50:65]
	ds_read2_b32 v[158:159], v100 offset0:22 offset1:23
	ds_read2_b32 v[160:161], v100 offset0:54 offset1:55
	s_setprio 0
	s_waitcnt lgkmcnt(0)
	s_nop 10
	v_add_f32_e32 v107, v34, v130
	v_add_f32_e32 v106, v35, v131
	v_add_f32_e32 v110, v50, v132
	v_add_f32_e32 v105, v51, v133
	v_add_f32_e32 v103, v36, v134
	v_add_f32_e32 v51, v37, v135
	v_add_f32_e32 v104, v52, v136
	v_add_f32_e32 v50, v53, v137
	v_add_f32_e32 v52, v38, v138
	v_add_f32_e32 v37, v39, v139
	v_add_f32_e32 v53, v54, v140
	v_add_f32_e32 v36, v55, v141
	v_add_f32_e32 v40, v40, v142
	v_add_f32_e32 v111, v41, v143
	v_add_f32_e32 v112, v56, v144
	v_add_f32_e32 v108, v57, v145
	v_add_f32_e32 v109, v42, v146
	v_add_f32_e32 v57, v43, v147
	v_add_f32_e32 v58, v58, v148
	v_add_f32_e32 v56, v59, v149
	v_add_f32_e32 v54, v44, v150
	v_add_f32_e32 v43, v45, v151
	v_add_f32_e32 v42, v61, v153
	v_add_f32_e32 v55, v60, v152
	v_add_f32_e32 v44, v46, v154
	v_add_f32_e32 v39, v47, v155
	v_add_f32_e32 v45, v62, v156
	v_add_f32_e32 v38, v63, v157
	v_add_f32_e32 v41, v48, v158
	v_max_f32_e32 v34, v106, v105
	v_add_f32_e32 v47, v49, v159
	v_max3_f32 v34, v107, v110, v34
	v_max_f32_e32 v35, v103, v104
	v_max_f32_e32 v49, v51, v50
	v_max3_f32 v34, v34, v35, v49
	v_max_f32_e32 v35, v52, v53
	v_max_f32_e32 v49, v37, v36
	v_max3_f32 v34, v34, v35, v49
	v_max_f32_e32 v35, v40, v112
	v_max_f32_e32 v49, v111, v108
	v_max3_f32 v34, v34, v35, v49
	v_max_f32_e32 v35, v109, v58
	v_max_f32_e32 v49, v57, v56
	v_max3_f32 v34, v34, v35, v49
	v_max_f32_e32 v35, v54, v55
	v_max_f32_e32 v49, v43, v42
	v_add_f32_e32 v48, v64, v160
	v_add_f32_e32 v46, v65, v161
	v_max3_f32 v34, v34, v35, v49
	v_max_f32_e32 v35, v44, v45
	v_max_f32_e32 v49, v39, v38
	v_max3_f32 v34, v34, v35, v49
	v_max_f32_e32 v35, v41, v48
	v_max_f32_e32 v49, v47, v46
	v_max3_f32 v34, v34, v35, v49
	v_mov_b32_e32 v35, v34
	s_nop 1
	v_permlane32_swap_b32_e32 v34, v35
	v_max3_f32 v35, v102, v34, v35
	v_sub_f32_e32 v34, v102, v35
	v_exp_f32_e32 v34, v34
	v_cmp_gt_f32_e32 vcc, v35, v102
	s_cbranch_vccz .LBB0_523
	v_pk_mul_f32 v[16:17], v[16:17], v[34:35] op_sel_hi:[1,0]
	v_pk_mul_f32 v[14:15], v[14:15], v[34:35] op_sel_hi:[1,0]
	v_pk_mul_f32 v[12:13], v[12:13], v[34:35] op_sel_hi:[1,0]
	v_pk_mul_f32 v[10:11], v[10:11], v[34:35] op_sel_hi:[1,0]
	v_pk_mul_f32 v[8:9], v[8:9], v[34:35] op_sel_hi:[1,0]
	v_pk_mul_f32 v[6:7], v[6:7], v[34:35] op_sel_hi:[1,0]
	v_pk_mul_f32 v[4:5], v[4:5], v[34:35] op_sel_hi:[1,0]
	v_pk_mul_f32 v[2:3], v[2:3], v[34:35] op_sel_hi:[1,0]
	v_pk_mul_f32 v[32:33], v[32:33], v[34:35] op_sel_hi:[1,0]
	v_pk_mul_f32 v[30:31], v[30:31], v[34:35] op_sel_hi:[1,0]
	v_pk_mul_f32 v[28:29], v[28:29], v[34:35] op_sel_hi:[1,0]
	v_pk_mul_f32 v[26:27], v[26:27], v[34:35] op_sel_hi:[1,0]
	v_pk_mul_f32 v[24:25], v[24:25], v[34:35] op_sel_hi:[1,0]
	v_pk_mul_f32 v[22:23], v[22:23], v[34:35] op_sel_hi:[1,0]
	v_pk_mul_f32 v[20:21], v[20:21], v[34:35] op_sel_hi:[1,0]
	v_pk_mul_f32 v[18:19], v[18:19], v[34:35] op_sel_hi:[1,0]
